# baseline (speedup 1.0000x reference)
; __device__ __forceinline__ void prep_phase(const Params& p, float* tile) {
;     ...
;       int kg = tid >> 7, col = tid & 127, n = nc * 128 + col;
;       const float* w = p.ada_w + ((size_t)li * D + kg * 256) * MODW + n;
;       const float* sk = sl + kg * 256;
;       float a0 = 0, a1 = 0, a2 = 0, a3 = 0, a4 = 0, a5 = 0, a6 = 0, a7 = 0, a8 = 0;
; #pragma unroll 8
;       for (int k = 0; k < 256; k++) {
;         float wv = w[(size_t)k * MODW];
;         a0 += sk[k] * wv; a1 += sk[1024 + k] * wv; a2 += sk[2048 + k] * wv; a3 += sk[3072 + k] * wv;
;         a4 += sk[4096 + k] * wv; a5 += sk[5120 + k] * wv; a6 += sk[6144 + k] * wv; a7 += sk[7168 + k] * wv;
;         a8 += sk[8192 + k] * wv;
;       }
.LBB0_54:
	v_lshl_add_u64 v[50:51], v[40:41], 0, s[14:15]
	global_load_dword v128, v[50:51], off
	v_add_co_u32_e32 v114, vcc, 0x9000, v50
	s_nop 1
	v_addc_co_u32_e32 v115, vcc, 0, v51, vcc
	global_load_dword v129, v[114:115], off
	v_add_co_u32_e32 v116, vcc, 0x12000, v50
	s_nop 1
	v_addc_co_u32_e32 v117, vcc, 0, v51, vcc
	global_load_dword v130, v[116:117], off
	v_add_co_u32_e32 v118, vcc, 0x1b000, v50
	s_nop 1
	v_addc_co_u32_e32 v119, vcc, 0, v51, vcc
	global_load_dword v131, v[118:119], off
	v_add_co_u32_e32 v120, vcc, 0x24000, v50
	s_nop 1
	v_addc_co_u32_e32 v121, vcc, 0, v51, vcc
	global_load_dword v132, v[120:121], off
	v_add_co_u32_e32 v122, vcc, 0x2d000, v50
	s_nop 1
	v_addc_co_u32_e32 v123, vcc, 0, v51, vcc
	global_load_dword v133, v[122:123], off
	v_add_co_u32_e32 v124, vcc, 0x36000, v50
	s_nop 1
	v_addc_co_u32_e32 v125, vcc, 0, v51, vcc
	global_load_dword v134, v[124:125], off
	v_add_co_u32_e32 v126, vcc, 0x3f000, v50
	s_nop 1
	v_addc_co_u32_e32 v127, vcc, 0, v51, vcc
	global_load_dword v135, v[126:127], off
	v_add_co_u32_e32 v144, vcc, 0x48000, v50
	s_nop 1
	v_addc_co_u32_e32 v145, vcc, 0, v51, vcc
	global_load_dword v136, v[144:145], off
	v_add_co_u32_e32 v146, vcc, 0x51000, v50
	s_nop 1
	v_addc_co_u32_e32 v147, vcc, 0, v51, vcc
	global_load_dword v137, v[146:147], off
	v_add_co_u32_e32 v148, vcc, 0x5a000, v50
	s_nop 1
	v_addc_co_u32_e32 v149, vcc, 0, v51, vcc
	global_load_dword v138, v[148:149], off
	v_add_co_u32_e32 v150, vcc, 0x63000, v50
	s_nop 1
	v_addc_co_u32_e32 v151, vcc, 0, v51, vcc
	global_load_dword v139, v[150:151], off
	v_add_co_u32_e32 v152, vcc, 0x6c000, v50
	s_nop 1
	v_addc_co_u32_e32 v153, vcc, 0, v51, vcc
	global_load_dword v140, v[152:153], off
	v_add_co_u32_e32 v154, vcc, 0x75000, v50
	s_nop 1
	v_addc_co_u32_e32 v155, vcc, 0, v51, vcc
	global_load_dword v141, v[154:155], off
	v_add_co_u32_e32 v156, vcc, 0x7e000, v50
	s_nop 1
	v_addc_co_u32_e32 v157, vcc, 0, v51, vcc
	global_load_dword v142, v[156:157], off
	v_add_co_u32_e32 v158, vcc, 0x87000, v50
	s_nop 1
	v_addc_co_u32_e32 v159, vcc, 0, v51, vcc
	global_load_dword v143, v[158:159], off
	ds_read_b128 v[72:75], v70
	ds_read_b128 v[0:3], v70 offset:16
	ds_read_b128 v[76:79], v70 offset:4096
	s_mov_b32 s20, 0x12000
	s_add_u32 s14, s14, 0x48000
	s_waitcnt lgkmcnt(2)
	v_mov_b32_e32 v80, v72
	s_addc_u32 s15, s15, 0
	s_waitcnt lgkmcnt(0)
	v_mov_b32_e32 v81, v76
	v_mov_b32_e32 v76, v73
	s_cmp_eq_u32 s14, 0x900000
	s_waitcnt vmcnt(15)
	v_mov_b32_e32 v4, v128
	v_pk_fma_f32 v[104:105], v[4:5], v[80:81], v[48:49] op_sel_hi:[0,1,1]
	ds_read_b128 v[80:83], v70 offset:8192
	ds_read_b128 v[84:87], v70 offset:12288
	s_waitcnt lgkmcnt(1)
	v_mov_b32_e32 v48, v80
	s_waitcnt lgkmcnt(0)
	v_mov_b32_e32 v49, v84
	v_pk_fma_f32 v[106:107], v[4:5], v[48:49], v[46:47] op_sel_hi:[0,1,1]
	ds_read_b128 v[46:49], v70 offset:16384
	ds_read_b128 v[88:91], v70 offset:20480
	ds_read_b128 v[92:95], v70 offset:24576
	ds_read_b128 v[96:99], v70 offset:28672
	v_mov_b32_e32 v84, v81
	s_waitcnt lgkmcnt(3)
	v_mov_b32_e32 v108, v46
	s_waitcnt lgkmcnt(1)
	v_mov_b32_e32 v101, v92
	s_waitcnt lgkmcnt(0)
	v_mov_b32_e32 v100, v96
	v_pk_fma_f32 v[44:45], v[4:5], v[100:101], v[44:45] op_sel_hi:[0,1,1]
	ds_read_b128 v[100:103], v70 offset:32768
	v_fmac_f32_e32 v39, v4, v88
	v_mov_b32_e32 v92, v97
	s_waitcnt lgkmcnt(0)
	v_mov_b32_e32 v109, v100
	v_pk_fma_f32 v[42:43], v[4:5], v[108:109], v[42:43] op_sel_hi:[0,1,1]
	v_add_co_u32_e32 v108, vcc, s17, v50
	v_mov_b32_e32 v100, v47
	s_nop 0
	v_addc_co_u32_e32 v109, vcc, 0, v51, vcc
	v_add_co_u32_e32 v46, vcc, s20, v50
	s_mov_b32 s20, 0x1b000
	s_nop 0
	v_addc_co_u32_e32 v47, vcc, 0, v51, vcc
	s_waitcnt vmcnt(14)
	v_mov_b32_e32 v4, v129
	v_pk_fma_f32 v[72:73], v[4:5], v[76:77], v[104:105] op_sel_hi:[0,1,1]
	v_pk_fma_f32 v[76:77], v[4:5], v[84:85], v[106:107] op_sel_hi:[0,1,1]
	v_fmac_f32_e32 v39, v4, v89
	v_pk_fma_f32 v[44:45], v[4:5], v[92:93], v[44:45] op_sel_hi:[0,1,1]
	v_pk_fma_f32 v[42:43], v[4:5], v[100:101], v[42:43] op_sel_hi:[0,1,1]
	v_mov_b32_e32 v46, v74
	v_mov_b32_e32 v47, v78
	v_mov_b32_e32 v78, v75
	s_waitcnt vmcnt(13)
	v_mov_b32_e32 v4, v130
	v_pk_fma_f32 v[46:47], v[4:5], v[46:47], v[72:73] op_sel_hi:[0,1,1]
	v_mov_b32_e32 v72, v82
	v_mov_b32_e32 v73, v86
	v_pk_fma_f32 v[72:73], v[4:5], v[72:73], v[76:77] op_sel_hi:[0,1,1]
	v_mov_b32_e32 v76, v98
	v_mov_b32_e32 v77, v94
	v_pk_fma_f32 v[44:45], v[4:5], v[76:77], v[44:45] op_sel_hi:[0,1,1]
	v_mov_b32_e32 v76, v48
	v_mov_b32_e32 v77, v102
	v_pk_fma_f32 v[42:43], v[4:5], v[76:77], v[42:43] op_sel_hi:[0,1,1]
	v_add_co_u32_e32 v76, vcc, s20, v50
	v_fmac_f32_e32 v39, v4, v90
	s_nop 0
	v_addc_co_u32_e32 v77, vcc, 0, v51, vcc
	s_mov_b32 s20, 0x24000
	v_add_co_u32_e32 v48, vcc, s20, v50
	v_mov_b32_e32 v86, v83
	v_mov_b32_e32 v94, v99
	v_mov_b32_e32 v102, v49
	v_addc_co_u32_e32 v49, vcc, 0, v51, vcc
	s_mov_b32 s20, 0x2d000
	s_waitcnt vmcnt(12)
	v_mov_b32_e32 v4, v131
	v_pk_fma_f32 v[76:77], v[4:5], v[78:79], v[46:47] op_sel_hi:[0,1,1]
	v_pk_fma_f32 v[46:47], v[4:5], v[86:87], v[72:73] op_sel_hi:[0,1,1]
	v_fmac_f32_e32 v39, v4, v91
	v_pk_fma_f32 v[44:45], v[4:5], v[94:95], v[44:45] op_sel_hi:[0,1,1]
	v_pk_fma_f32 v[42:43], v[4:5], v[102:103], v[42:43] op_sel_hi:[0,1,1]
	ds_read_b128 v[72:75], v70 offset:4112
	v_mov_b32_e32 v48, v0
	s_waitcnt lgkmcnt(0)
	v_mov_b32_e32 v49, v72
	v_mov_b32_e32 v72, v1
	s_waitcnt vmcnt(11)
	v_mov_b32_e32 v4, v132
	v_pk_fma_f32 v[48:49], v[4:5], v[48:49], v[76:77] op_sel_hi:[0,1,1]
	ds_read_b128 v[76:79], v70 offset:8208
	ds_read_b128 v[80:83], v70 offset:12304
	s_waitcnt lgkmcnt(1)
	v_mov_b32_e32 v84, v76
	s_waitcnt lgkmcnt(0)
; __device__ __forceinline__ void prep_phase(const Params& p, float* tile) {
;     ...
;       for (int k = 0; k < 256; k++) {
;         float wv = w[(size_t)k * MODW];
;         a0 += sk[k] * wv; a1 += sk[1024 + k] * wv; a2 += sk[2048 + k] * wv; a3 += sk[3072 + k] * wv;
;         a4 += sk[4096 + k] * wv; a5 += sk[5120 + k] * wv; a6 += sk[6144 + k] * wv; a7 += sk[7168 + k] * wv;
;         a8 += sk[8192 + k] * wv;
;       }
	v_mov_b32_e32 v85, v80
	v_pk_fma_f32 v[46:47], v[4:5], v[84:85], v[46:47] op_sel_hi:[0,1,1]
	ds_read_b128 v[84:87], v70 offset:16400
	ds_read_b128 v[88:91], v70 offset:20496
	ds_read_b128 v[92:95], v70 offset:24592
	ds_read_b128 v[96:99], v70 offset:28688
	v_mov_b32_e32 v80, v77
	s_waitcnt lgkmcnt(3)
	v_mov_b32_e32 v104, v84
	s_waitcnt lgkmcnt(1)
	v_mov_b32_e32 v101, v92
	s_waitcnt lgkmcnt(0)
	v_mov_b32_e32 v100, v96
	v_pk_fma_f32 v[44:45], v[4:5], v[100:101], v[44:45] op_sel_hi:[0,1,1]
	ds_read_b128 v[100:103], v70 offset:32784
	v_fmac_f32_e32 v39, v4, v88
	v_mov_b32_e32 v92, v97
	v_add_u32_e32 v70, 32, v70
	s_waitcnt lgkmcnt(0)
	v_mov_b32_e32 v105, v100
	v_pk_fma_f32 v[42:43], v[4:5], v[104:105], v[42:43] op_sel_hi:[0,1,1]
	v_add_co_u32_e32 v104, vcc, s20, v50
	v_mov_b32_e32 v100, v85
	s_nop 0
	v_addc_co_u32_e32 v105, vcc, 0, v51, vcc
	s_mov_b32 s20, 0x36000
	s_waitcnt vmcnt(10)
	v_mov_b32_e32 v0, v133
	v_pk_fma_f32 v[48:49], v[0:1], v[72:73], v[48:49] op_sel_hi:[0,1,1]
	v_pk_fma_f32 v[46:47], v[0:1], v[80:81], v[46:47] op_sel_hi:[0,1,1]
	v_fmac_f32_e32 v39, v0, v89
	v_pk_fma_f32 v[44:45], v[0:1], v[92:93], v[44:45] op_sel_hi:[0,1,1]
	v_pk_fma_f32 v[0:1], v[0:1], v[100:101], v[42:43] op_sel_hi:[0,1,1]
	v_add_co_u32_e32 v42, vcc, s20, v50
	s_mov_b32 s20, 0x3f000
	s_nop 0
	v_addc_co_u32_e32 v43, vcc, 0, v51, vcc
	v_mov_b32_e32 v42, v2
	v_mov_b32_e32 v43, v74
	v_mov_b32_e32 v74, v3
	s_waitcnt vmcnt(9)
	v_mov_b32_e32 v4, v134
	v_pk_fma_f32 v[42:43], v[4:5], v[42:43], v[48:49] op_sel_hi:[0,1,1]
	v_mov_b32_e32 v48, v78
	v_mov_b32_e32 v49, v82
	v_pk_fma_f32 v[46:47], v[4:5], v[48:49], v[46:47] op_sel_hi:[0,1,1]
	v_mov_b32_e32 v48, v98
	v_mov_b32_e32 v49, v94
	v_pk_fma_f32 v[44:45], v[4:5], v[48:49], v[44:45] op_sel_hi:[0,1,1]
	v_mov_b32_e32 v48, v86
	v_mov_b32_e32 v49, v102
	v_pk_fma_f32 v[0:1], v[4:5], v[48:49], v[0:1] op_sel_hi:[0,1,1]
	v_add_co_u32_e32 v48, vcc, s20, v50
	v_fmac_f32_e32 v39, v4, v90
	s_nop 0
	v_addc_co_u32_e32 v49, vcc, 0, v51, vcc
	v_mov_b32_e32 v82, v79
	v_mov_b32_e32 v94, v99
	v_mov_b32_e32 v102, v87
	s_waitcnt vmcnt(8)
	v_mov_b32_e32 v2, v135
	v_pk_fma_f32 v[48:49], v[2:3], v[74:75], v[42:43] op_sel_hi:[0,1,1]
	v_pk_fma_f32 v[46:47], v[2:3], v[82:83], v[46:47] op_sel_hi:[0,1,1]
	v_fmac_f32_e32 v39, v2, v91
	v_pk_fma_f32 v[44:45], v[2:3], v[94:95], v[44:45] op_sel_hi:[0,1,1]
	v_pk_fma_f32 v[42:43], v[2:3], v[102:103], v[0:1] op_sel_hi:[0,1,1]
	v_lshl_add_u64 v[50:51], v[40:41], 0, s[14:15]
	ds_read_b128 v[72:75], v70
	ds_read_b128 v[0:3], v70 offset:16
	ds_read_b128 v[76:79], v70 offset:4096
	s_mov_b32 s20, 0x12000
	s_add_u32 s14, s14, 0x48000
	s_waitcnt lgkmcnt(2)
	v_mov_b32_e32 v80, v72
	s_addc_u32 s15, s15, 0
	s_waitcnt lgkmcnt(0)
	v_mov_b32_e32 v81, v76
	v_mov_b32_e32 v76, v73
	s_cmp_eq_u32 s14, 0x900000
	s_waitcnt vmcnt(7)
	v_mov_b32_e32 v4, v136
	v_pk_fma_f32 v[104:105], v[4:5], v[80:81], v[48:49] op_sel_hi:[0,1,1]
	ds_read_b128 v[80:83], v70 offset:8192
	ds_read_b128 v[84:87], v70 offset:12288
	s_waitcnt lgkmcnt(1)
	v_mov_b32_e32 v48, v80
	s_waitcnt lgkmcnt(0)
	v_mov_b32_e32 v49, v84
	v_pk_fma_f32 v[106:107], v[4:5], v[48:49], v[46:47] op_sel_hi:[0,1,1]
	ds_read_b128 v[46:49], v70 offset:16384
	ds_read_b128 v[88:91], v70 offset:20480
	ds_read_b128 v[92:95], v70 offset:24576
	ds_read_b128 v[96:99], v70 offset:28672
	v_mov_b32_e32 v84, v81
	s_waitcnt lgkmcnt(3)
	v_mov_b32_e32 v108, v46
	s_waitcnt lgkmcnt(1)
	v_mov_b32_e32 v101, v92
	s_waitcnt lgkmcnt(0)
	v_mov_b32_e32 v100, v96
	v_pk_fma_f32 v[44:45], v[4:5], v[100:101], v[44:45] op_sel_hi:[0,1,1]
	ds_read_b128 v[100:103], v70 offset:32768
	v_fmac_f32_e32 v39, v4, v88
	v_mov_b32_e32 v92, v97
	s_waitcnt lgkmcnt(0)
	v_mov_b32_e32 v109, v100
	v_pk_fma_f32 v[42:43], v[4:5], v[108:109], v[42:43] op_sel_hi:[0,1,1]
	v_add_co_u32_e32 v108, vcc, s17, v50
	v_mov_b32_e32 v100, v47
	s_nop 0
	v_addc_co_u32_e32 v109, vcc, 0, v51, vcc
	v_add_co_u32_e32 v46, vcc, s20, v50
	s_mov_b32 s20, 0x1b000
	s_nop 0
	v_addc_co_u32_e32 v47, vcc, 0, v51, vcc
	s_waitcnt vmcnt(6)
	v_mov_b32_e32 v4, v137
	v_pk_fma_f32 v[72:73], v[4:5], v[76:77], v[104:105] op_sel_hi:[0,1,1]
	v_pk_fma_f32 v[76:77], v[4:5], v[84:85], v[106:107] op_sel_hi:[0,1,1]
	v_fmac_f32_e32 v39, v4, v89
	v_pk_fma_f32 v[44:45], v[4:5], v[92:93], v[44:45] op_sel_hi:[0,1,1]
	v_pk_fma_f32 v[42:43], v[4:5], v[100:101], v[42:43] op_sel_hi:[0,1,1]
	v_mov_b32_e32 v46, v74
	v_mov_b32_e32 v47, v78
	v_mov_b32_e32 v78, v75
	s_waitcnt vmcnt(5)
; __device__ __forceinline__ void prep_phase(const Params& p, float* tile) {
;     ...
;       for (int k = 0; k < 256; k++) {
;         float wv = w[(size_t)k * MODW];
;         a0 += sk[k] * wv; a1 += sk[1024 + k] * wv; a2 += sk[2048 + k] * wv; a3 += sk[3072 + k] * wv;
;         a4 += sk[4096 + k] * wv; a5 += sk[5120 + k] * wv; a6 += sk[6144 + k] * wv; a7 += sk[7168 + k] * wv;
;         a8 += sk[8192 + k] * wv;
;       }
;       float* rr = red + (kg * 9) * 128 + col;
;       rr[0] = a0; rr[128] = a1; rr[256] = a2; rr[384] = a3; rr[512] = a4; rr[640] = a5; rr[768] = a6; rr[896] = a7; rr[1024] = a8;
;       __syncthreads();
;       for (int e = tid; e < 9 * 128; e += 512) {
;         int r = e >> 7, c2 = e & 127;
;         float v = p.ada_b[li * MODW + nc * 128 + c2] + red[(0 * 9 + r) * 128 + c2] + red[(1 * 9 + r) * 128 + c2] +
;                   red[(2 * 9 + r) * 128 + c2] + red[(3 * 9 + r) * 128 + c2];
;         p.mod[(size_t)(li * 9 + r) * MODW + nc * 128 + c2] = v;
	v_mov_b32_e32 v4, v138
	v_pk_fma_f32 v[46:47], v[4:5], v[46:47], v[72:73] op_sel_hi:[0,1,1]
	v_mov_b32_e32 v72, v82
	v_mov_b32_e32 v73, v86
	v_pk_fma_f32 v[72:73], v[4:5], v[72:73], v[76:77] op_sel_hi:[0,1,1]
	v_mov_b32_e32 v76, v98
	v_mov_b32_e32 v77, v94
	v_pk_fma_f32 v[44:45], v[4:5], v[76:77], v[44:45] op_sel_hi:[0,1,1]
	v_mov_b32_e32 v76, v48
	v_mov_b32_e32 v77, v102
	v_pk_fma_f32 v[42:43], v[4:5], v[76:77], v[42:43] op_sel_hi:[0,1,1]
	v_add_co_u32_e32 v76, vcc, s20, v50
	v_fmac_f32_e32 v39, v4, v90
	s_nop 0
	v_addc_co_u32_e32 v77, vcc, 0, v51, vcc
	s_mov_b32 s20, 0x24000
	v_add_co_u32_e32 v48, vcc, s20, v50
	v_mov_b32_e32 v86, v83
	v_mov_b32_e32 v94, v99
	v_mov_b32_e32 v102, v49
	v_addc_co_u32_e32 v49, vcc, 0, v51, vcc
	s_mov_b32 s20, 0x2d000
	s_waitcnt vmcnt(4)
	v_mov_b32_e32 v4, v139
	v_pk_fma_f32 v[76:77], v[4:5], v[78:79], v[46:47] op_sel_hi:[0,1,1]
	v_pk_fma_f32 v[46:47], v[4:5], v[86:87], v[72:73] op_sel_hi:[0,1,1]
	v_fmac_f32_e32 v39, v4, v91
	v_pk_fma_f32 v[44:45], v[4:5], v[94:95], v[44:45] op_sel_hi:[0,1,1]
	v_pk_fma_f32 v[42:43], v[4:5], v[102:103], v[42:43] op_sel_hi:[0,1,1]
	ds_read_b128 v[72:75], v70 offset:4112
	v_mov_b32_e32 v48, v0
	s_waitcnt lgkmcnt(0)
	v_mov_b32_e32 v49, v72
	v_mov_b32_e32 v72, v1
	s_waitcnt vmcnt(3)
	v_mov_b32_e32 v4, v140
	v_pk_fma_f32 v[48:49], v[4:5], v[48:49], v[76:77] op_sel_hi:[0,1,1]
	ds_read_b128 v[76:79], v70 offset:8208
	ds_read_b128 v[80:83], v70 offset:12304
	s_waitcnt lgkmcnt(1)
	v_mov_b32_e32 v84, v76
	s_waitcnt lgkmcnt(0)
	v_mov_b32_e32 v85, v80
	v_pk_fma_f32 v[46:47], v[4:5], v[84:85], v[46:47] op_sel_hi:[0,1,1]
	ds_read_b128 v[84:87], v70 offset:16400
	ds_read_b128 v[88:91], v70 offset:20496
	ds_read_b128 v[92:95], v70 offset:24592
	ds_read_b128 v[96:99], v70 offset:28688
	v_mov_b32_e32 v80, v77
	s_waitcnt lgkmcnt(3)
	v_mov_b32_e32 v104, v84
	s_waitcnt lgkmcnt(1)
	v_mov_b32_e32 v101, v92
	s_waitcnt lgkmcnt(0)
	v_mov_b32_e32 v100, v96
	v_pk_fma_f32 v[44:45], v[4:5], v[100:101], v[44:45] op_sel_hi:[0,1,1]
	ds_read_b128 v[100:103], v70 offset:32784
	v_fmac_f32_e32 v39, v4, v88
	v_mov_b32_e32 v92, v97
	v_add_u32_e32 v70, 32, v70
	s_waitcnt lgkmcnt(0)
	v_mov_b32_e32 v105, v100
	v_pk_fma_f32 v[42:43], v[4:5], v[104:105], v[42:43] op_sel_hi:[0,1,1]
	v_add_co_u32_e32 v104, vcc, s20, v50
	v_mov_b32_e32 v100, v85
	s_nop 0
	v_addc_co_u32_e32 v105, vcc, 0, v51, vcc
	s_mov_b32 s20, 0x36000
	s_waitcnt vmcnt(2)
	v_mov_b32_e32 v0, v141
	v_pk_fma_f32 v[48:49], v[0:1], v[72:73], v[48:49] op_sel_hi:[0,1,1]
	v_pk_fma_f32 v[46:47], v[0:1], v[80:81], v[46:47] op_sel_hi:[0,1,1]
	v_fmac_f32_e32 v39, v0, v89
	v_pk_fma_f32 v[44:45], v[0:1], v[92:93], v[44:45] op_sel_hi:[0,1,1]
	v_pk_fma_f32 v[0:1], v[0:1], v[100:101], v[42:43] op_sel_hi:[0,1,1]
	v_add_co_u32_e32 v42, vcc, s20, v50
	s_mov_b32 s20, 0x3f000
	s_nop 0
	v_addc_co_u32_e32 v43, vcc, 0, v51, vcc
	v_mov_b32_e32 v42, v2
	v_mov_b32_e32 v43, v74
	v_mov_b32_e32 v74, v3
	s_waitcnt vmcnt(1)
	v_mov_b32_e32 v4, v142
	v_pk_fma_f32 v[42:43], v[4:5], v[42:43], v[48:49] op_sel_hi:[0,1,1]
	v_mov_b32_e32 v48, v78
	v_mov_b32_e32 v49, v82
	v_pk_fma_f32 v[46:47], v[4:5], v[48:49], v[46:47] op_sel_hi:[0,1,1]
	v_mov_b32_e32 v48, v98
	v_mov_b32_e32 v49, v94
	v_pk_fma_f32 v[44:45], v[4:5], v[48:49], v[44:45] op_sel_hi:[0,1,1]
	v_mov_b32_e32 v48, v86
	v_mov_b32_e32 v49, v102
	v_pk_fma_f32 v[0:1], v[4:5], v[48:49], v[0:1] op_sel_hi:[0,1,1]
	v_add_co_u32_e32 v48, vcc, s20, v50
	v_fmac_f32_e32 v39, v4, v90
	s_nop 0
	v_addc_co_u32_e32 v49, vcc, 0, v51, vcc
	v_mov_b32_e32 v82, v79
	v_mov_b32_e32 v94, v99
	v_mov_b32_e32 v102, v87
	s_waitcnt vmcnt(0)
	v_mov_b32_e32 v2, v143
	v_pk_fma_f32 v[48:49], v[2:3], v[74:75], v[42:43] op_sel_hi:[0,1,1]
	v_pk_fma_f32 v[46:47], v[2:3], v[82:83], v[46:47] op_sel_hi:[0,1,1]
	v_fmac_f32_e32 v39, v2, v91
	v_pk_fma_f32 v[44:45], v[2:3], v[94:95], v[44:45] op_sel_hi:[0,1,1]
	v_pk_fma_f32 v[42:43], v[2:3], v[102:103], v[0:1] op_sel_hi:[0,1,1]
	s_cbranch_scc0 .LBB0_54
	ds_write2st64_b32 v13, v48, v49 offset0:144 offset1:146
	ds_write2st64_b32 v13, v46, v47 offset0:148 offset1:150
	ds_write2st64_b32 v13, v42, v39 offset0:152 offset1:154
	ds_write2st64_b32 v13, v45, v44 offset0:156 offset1:158
	ds_write_b32 v13, v43 offset:40960
	s_waitcnt lgkmcnt(0)
	s_barrier
	s_and_saveexec_b64 s[14:15], s[4:5]
	s_load_dwordx16 s[40:55], s[0:1], 0x0
	s_cbranch_execz .LBB0_58
	s_mul_i32 s30, s18, 0x2400
	s_add_i32 s30, s30, s19
	s_mul_i32 s31, s18, 9
	s_lshl_b32 s18, s19, 2
	s_add_u32 s18, s76, s18
	s_addc_u32 s19, s77, 0
	s_mov_b64 s[20:21], 0
	v_mov_b32_e32 v0, v69
	v_mov_b32_e32 v1, v6
